# asymmetric v-side priority: waves 0-3 s_setprio 2, waves 4-7 s_setprio 3 (one wave per SIMD runs ahead)
# speedup vs baseline: 1.0054x; 1.0054x over previous
; __device__ void phase_gather(const Params& p) {
;   const int tid = threadIdx.x, lane = tid & 63, wid = tid >> 6;
;   unsigned char* ws = p.ws;
;   const unsigned char* ub = ws + OFF_XB;
;   const unsigned char* vb = ws + OFF_XB + 16 * MIB;
;   const float* scales = (const float*)(ws + OFF_SCALES);
;   const int* idxg = (const int*)(ws + OFF_IDX);
;   const float* gg = (const float*)(ws + OFF_G);
;   const float* ssq2 = (const float*)(ws + OFF_SSQ2);
;   const bool b5 = (lane & 32) != 0, b4 = (lane & 16) != 0, b3 = (lane & 8) != 0;
;   const int srcl = ((lane & 1) << 3) | (((lane >> 1) & 1) << 4) | (((lane >> 2) & 1) << 5);
;   for (int t = blockIdx.x * 8 + wid; t < T_TOK; t += gridDim.x * 8) {
;     const int id0 = idxg[(size_t)t * 128 + lane], id1 = idxg[(size_t)t * 128 + 64 + lane];
;     const float g0 = gg[(size_t)t * 128 + lane], g1 = gg[(size_t)t * 128 + 64 + lane];
;     const float su0 = scales[id0], su1 = scales[id1], sv0 = scales[16384 + id0], sv1 = scales[16384 + id1];
;     float* orow = p.out + (size_t)t * DM + lane * 32;
;     const float sx = ((const float*)(ws + OFF_WBUF + 8 * MIB))[t];
;     float sq = (lane < 32) ? ssq2[(size_t)t * 32 + lane] : 0.f;
;     sq = wave_sum(sq);
;     const float rs2 = rsqrtf(sq * (1.f / 2048.f) + EPSV);
;     const int* wbuf = (const int*)(ws + OFF_WBUF);
.LBB0_1316:
	s_waitcnt vmcnt(0)
	s_setprio 2
	s_cmp_lt_u32 s60, 0x1000
	s_cbranch_scc1 .Lvs_prio_done
	s_setprio 3
.Lvs_prio_done:
	s_and_saveexec_b64 s[2:3], s[0:1]
	s_cbranch_execz .LBB0_1323
	s_add_u32 s0, s34, 0x1dc90000
	s_addc_u32 s1, s35, 0
	v_writelane_b32 v250, s0, 20
	v_lshlrev_b32_e32 v0, 2, v138
	v_mov_b32_e32 v1, 0
	v_writelane_b32 v250, s1, 21
	s_add_u32 s0, s34, 0xc800000
	s_addc_u32 s1, s35, 0
	v_writelane_b32 v250, s0, 22
	v_cmp_lt_i32_e32 vcc, v89, v84
	v_lshl_add_u64 v[2:3], s[34:35], 0, v[0:1]
	v_writelane_b32 v250, s1, 23
	s_add_u32 s0, s34, 0x17c00000
	s_addc_u32 s1, s35, 0
	v_cndmask_b32_e32 v0, v83, v89, vcc
	v_cmp_lt_i32_e32 vcc, v90, v84
	v_writelane_b32 v250, s0, 24
	v_lshlrev_b32_e32 v126, 2, v0
	v_cndmask_b32_e32 v0, v83, v90, vcc
	v_cmp_lt_i32_e32 vcc, v88, v84
	v_writelane_b32 v250, s1, 25
	v_cmp_gt_u32_e64 s[0:1], 32, v138
	v_lshlrev_b32_e32 v127, 2, v0
	v_cndmask_b32_e32 v0, v83, v88, vcc
	v_cmp_lt_i32_e32 vcc, v87, v84
	v_writelane_b32 v250, s0, 26
	v_lshlrev_b32_e32 v128, 2, v0
	v_cndmask_b32_e32 v0, v83, v87, vcc
	v_cmp_lt_i32_e32 vcc, v86, v84
	v_writelane_b32 v250, s1, 27
	v_lshlrev_b32_e32 v129, 2, v0
	v_cndmask_b32_e32 v0, v83, v86, vcc
	v_cmp_lt_i32_e32 vcc, v85, v84
	s_mov_b64 s[0:1], 0x1da90000
	v_lshlrev_b32_e32 v130, 2, v0
	v_cndmask_b32_e32 v0, v83, v85, vcc
	v_writelane_b32 v250, s68, 28
	v_lshl_add_u64 v[114:115], v[2:3], 0, s[0:1]
	v_lshlrev_b32_e32 v131, 2, v0
	s_mov_b64 s[0:1], 0x1000000
	v_lshlrev_b32_e32 v0, 7, v138
	v_writelane_b32 v250, s69, 29
	v_and_b32_e32 v132, 24, v82
	v_lshl_add_u64 v[116:117], v[72:73], 0, s[0:1]
	v_lshl_add_u64 v[118:119], s[30:31], 0, v[0:1]
	v_lshl_add_u64 v[120:121], s[28:29], 0, v[0:1]
	global_load_dwordx4 v[188:191], v[120:121], off offset:16
	global_load_dwordx4 v[192:195], v[120:121], off offset:32
	global_load_dwordx4 v[196:199], v[120:121], off offset:48
	global_load_dwordx4 v[200:203], v[120:121], off offset:64
	global_load_dwordx4 v[204:207], v[120:121], off offset:80
	global_load_dwordx4 v[208:211], v[120:121], off offset:96
	global_load_dwordx4 v[212:215], v[120:121], off offset:112
	s_mov_b64 s[0:1], 0
	v_mov_b32_e32 v133, 0x358637bd
	s_mov_b32 s55, 0x800000
	s_mov_b32 s33, 0x5010400
	s_mov_b32 s52, 0x7030602
	s_mov_b32 s53, 0x5040100
	s_mov_b32 s54, 0x7060302
	v_writelane_b32 v250, s70, 30
	s_nop 1
	v_writelane_b32 v250, s71, 31
